# v19: v15 + cross-half row-sum reduction deferred to the end of the unit (per-lane partial l in the loop), alpha written straight into its carried register
# baseline (speedup 1.0000x reference)
.LBB0_526:
	ds_read_b128 v[64:67], v192 offset:49152
	ds_read_b128 v[68:71], v192 offset:57344
	ds_read_b128 v[232:235], v200 offset:49152
	ds_read_b128 v[236:239], v200 offset:57344
	ds_read_b128 v[250:253], v199 offset:49152
	ds_read_b128 v[244:247], v199 offset:57344
	ds_read_b128 v[212:215], v198 offset:49152
	ds_read_b128 v[216:219], v198 offset:57344
	v_add_f32_e32 v162, v163, v177
	s_waitcnt lgkmcnt(6)
	v_mfma_f32_32x32x16_bf16 v[80:95], v[64:67], v[118:121], 0
	v_add_f32_e32 v162, v164, v162
	v_add_f32_e32 v162, v207, v162
	v_add_f32_e32 v162, v176, v162
	v_add_f32_e32 v162, v210, v162
	v_mfma_f32_32x32x16_bf16 v[64:79], v[68:71], v[118:121], 0
	v_add_f32_e32 v162, v165, v162
	v_add_f32_e32 v162, v175, v162
	v_add_f32_e32 v162, v166, v162
	v_add_f32_e32 v162, v173, v162
	v_add_f32_e32 v162, v167, v162
	s_waitcnt lgkmcnt(4)
	v_mfma_f32_32x32x16_bf16 v[80:95], v[232:235], v[114:117], v[80:95]
	ds_read_b128 v[232:235], v195 offset:49152
	v_add_f32_e32 v162, v174, v162
	v_exp_f32_e32 v160, v160
	v_add_f32_e32 v162, v168, v162
	v_exp_f32_e32 v161, v161
	v_mfma_f32_32x32x16_bf16 v[64:79], v[236:239], v[114:117], v[64:79]
	ds_read_b128 v[236:239], v195 offset:57344
	v_add_f32_e32 v162, v171, v162
	v_exp_f32_e32 v158, v158
	v_add_f32_e32 v162, v169, v162
	v_exp_f32_e32 v159, v159
	s_waitcnt lgkmcnt(4)
	v_mfma_f32_32x32x16_bf16 v[80:95], v[250:253], v[126:129], v[80:95]
	ds_read_b128 v[250:253], v193 offset:49152
	v_add_f32_e32 v162, v172, v162
	v_exp_f32_e32 v154, v154
	v_add_f32_e32 v162, v160, v162
	v_exp_f32_e32 v155, v155
	v_mfma_f32_32x32x16_bf16 v[64:79], v[244:247], v[126:129], v[64:79]
	ds_read_b128 v[244:247], v193 offset:57344
	v_add_f32_e32 v162, v161, v162
	v_exp_f32_e32 v150, v150
	v_add_f32_e32 v162, v158, v162
	v_exp_f32_e32 v151, v151
	s_waitcnt lgkmcnt(4)
	v_mfma_f32_32x32x16_bf16 v[80:95], v[212:215], v[122:125], v[80:95]
	ds_read_b128 v[212:215], v202 offset:49152
	v_add_f32_e32 v162, v159, v162
	v_exp_f32_e32 v148, v148
	v_add_f32_e32 v162, v154, v162
	v_exp_f32_e32 v149, v149
	v_mfma_f32_32x32x16_bf16 v[64:79], v[216:219], v[122:125], v[64:79]
	ds_read_b128 v[216:219], v202 offset:57344
	v_add_f32_e32 v162, v155, v162
	v_exp_f32_e32 v156, v156
	v_add_f32_e32 v162, v150, v162
	v_exp_f32_e32 v157, v157
	s_waitcnt lgkmcnt(4)
	v_mfma_f32_32x32x16_bf16 v[80:95], v[232:235], v[110:113], v[80:95]
	ds_read_b128 v[232:235], v201 offset:49152
	v_add_f32_e32 v162, v151, v162
	v_exp_f32_e32 v152, v152
	v_add_f32_e32 v162, v148, v162
	v_exp_f32_e32 v153, v153
	v_mfma_f32_32x32x16_bf16 v[64:79], v[236:239], v[110:113], v[64:79]
	ds_read_b128 v[236:239], v201 offset:57344
	v_add_f32_e32 v162, v149, v162
	v_exp_f32_e32 v146, v146
	v_add_f32_e32 v162, v156, v162
	v_exp_f32_e32 v147, v147
	s_waitcnt lgkmcnt(4)
	v_mfma_f32_32x32x16_bf16 v[80:95], v[250:253], v[106:109], v[80:95]
	v_add_f32_e32 v162, v157, v162
	v_add_f32_e32 v162, v152, v162
	v_add_f32_e32 v162, v153, v162
	v_add_f32_e32 v162, v146, v162
	v_add_f32_e32 v204, v147, v162
	v_fma_f32 v185, v203, v185, v204
	v_mfma_f32_32x32x16_bf16 v[64:79], v[244:247], v[106:109], v[64:79]
	v_cvt_pk_bf16_f32 v162, v163, v177
	v_cvt_pk_bf16_f32 v163, v164, v207
	v_cvt_pk_bf16_f32 v164, v176, v210
	s_waitcnt lgkmcnt(2)
	v_mfma_f32_32x32x16_bf16 v[80:95], v[212:215], v[102:105], v[80:95]
	v_cvt_pk_bf16_f32 v165, v165, v175
	v_cvt_pk_bf16_f32 v166, v166, v173
	v_cvt_pk_bf16_f32 v167, v167, v174
	v_cvt_pk_bf16_f32 v168, v168, v171
	v_mfma_f32_32x32x16_bf16 v[64:79], v[216:219], v[102:105], v[64:79]
	v_cvt_pk_bf16_f32 v169, v169, v172
	v_cvt_pk_bf16_f32 v172, v160, v161
	v_cvt_pk_bf16_f32 v173, v158, v159
	v_cvt_pk_bf16_f32 v174, v154, v155
	ds_read_b64_tr_b16 v[210:211], v187 offset:0x0
	ds_read_b64_tr_b16 v[212:213], v187 offset:0x800
	ds_read_b64_tr_b16 v[214:215], v187 offset:0x200
	ds_read_b64_tr_b16 v[216:217], v187 offset:0xa00
	ds_read_b64_tr_b16 v[218:219], v187 offset:0x400
	ds_read_b64_tr_b16 v[220:221], v187 offset:0xc00
	ds_read_b64_tr_b16 v[222:223], v187 offset:0x600
	ds_read_b64_tr_b16 v[224:225], v187 offset:0xe00
	s_waitcnt lgkmcnt(8)
	v_mfma_f32_32x32x16_bf16 v[80:95], v[232:235], v[98:101], v[80:95]
	v_cvt_pk_bf16_f32 v175, v150, v151
	v_cvt_pk_bf16_f32 v206, v148, v149
	v_cvt_pk_bf16_f32 v207, v156, v157
	v_mfma_f32_32x32x16_bf16 v[64:79], v[236:239], v[98:101], v[64:79]
	v_cvt_pk_bf16_f32 v208, v152, v153
	v_cvt_pk_bf16_f32 v209, v146, v147
	s_waitcnt vmcnt(0)
	ds_write_b128 v188, v[134:137] offset:32768
	ds_write_b128 v189, v[142:145] offset:32768
	global_load_dwordx4 v[146:149], v178, s[66:67]
	global_load_dwordx4 v[150:153], v179, s[66:67]
	global_load_dwordx4 v[154:157], v178, s[98:99]
	global_load_dwordx4 v[158:161], v179, s[98:99]
	s_add_u32 s66, s66, 0x4000
	s_addc_u32 s67, s67, 0
	s_add_u32 s98, s98, 0x4000
	s_addc_u32 s99, s99, 0
	s_waitcnt lgkmcnt(6)
	v_mfma_f32_32x32x16_bf16 v[0:15], v[162:165], v[210:213], v[0:15]
	ds_read_b64_tr_b16 v[210:211], v187 offset:0x1000
	ds_read_b64_tr_b16 v[212:213], v187 offset:0x1800
	v_max_f32_e32 v240, v80, v81
	v_max3_f32 v240, v240, v82, v83
	v_max3_f32 v240, v240, v84, v85
	v_max3_f32 v240, v240, v86, v87
	v_max3_f32 v240, v240, v88, v89
	v_mfma_f32_32x32x16_bf16 v[48:63], v[162:165], v[214:217], v[48:63]
	ds_read_b64_tr_b16 v[214:215], v187 offset:0x1200
	ds_read_b64_tr_b16 v[216:217], v187 offset:0x1a00
	v_max3_f32 v240, v240, v90, v91
	v_max3_f32 v240, v240, v92, v93
	v_max3_f32 v240, v240, v94, v95
	v_max3_f32 v240, v240, v64, v65
	v_max3_f32 v240, v240, v66, v67
	v_max3_f32 v240, v240, v68, v69
	s_waitcnt lgkmcnt(6)
	v_mfma_f32_32x32x16_bf16 v[32:47], v[162:165], v[218:221], v[32:47]
	ds_read_b64_tr_b16 v[218:219], v187 offset:0x1400
	ds_read_b64_tr_b16 v[220:221], v187 offset:0x1c00
	v_max3_f32 v240, v240, v70, v71
	v_max3_f32 v240, v240, v72, v73
	v_max3_f32 v240, v240, v74, v75
	v_max3_f32 v240, v240, v76, v77
	v_max3_f32 v240, v240, v78, v79
	v_mfma_f32_32x32x16_bf16 v[16:31], v[162:165], v[222:225], v[16:31]
	ds_read_b64_tr_b16 v[222:223], v187 offset:0x1600
	ds_read_b64_tr_b16 v[224:225], v187 offset:0x1e00
	v_mov_b32_e32 v241, v240
	s_nop 1
	v_permlane32_swap_b32_e32 v240, v241
	v_max_f32_e32 v240, v240, v241
	v_sub_f32_e32 v241, v240, v243
	v_cmp_ge_f32_e32 vcc, s92, v241
	s_waitcnt lgkmcnt(4)
	v_mfma_f32_32x32x16_bf16 v[0:15], v[166:169], v[210:213], v[0:15]
	ds_read_b64_tr_b16 v[210:211], v187 offset:0x2000
	ds_read_b64_tr_b16 v[212:213], v187 offset:0x2800
	s_cmp_eq_u64 vcc, exec
	s_cselect_b64 s[42:43], -1, 0
	s_cbranch_scc1 .Lattn_common_a
	v_max_f32_e32 v240, v243, v240
	v_sub_f32_e32 v241, v243, v240
	v_mul_f32_e32 v241, 0x3e0293ee, v241
	v_exp_f32_e32 v241, v241
	v_mov_b32_e32 v243, v240
	v_mul_f32_e32 v242, 0xbe0293ee, v243

.LBB0_530:
	v_fmamk_f32 v217, v64, 0x3e0293ee, v242
	v_fmamk_f32 v218, v65, 0x3e0293ee, v242
	v_fmamk_f32 v219, v66, 0x3e0293ee, v242
	v_fmamk_f32 v220, v67, 0x3e0293ee, v242
	v_fmamk_f32 v221, v68, 0x3e0293ee, v242
	v_fmamk_f32 v210, v69, 0x3e0293ee, v242
	v_fmamk_f32 v211, v70, 0x3e0293ee, v242
	v_fmamk_f32 v212, v71, 0x3e0293ee, v242
	v_fmamk_f32 v213, v72, 0x3e0293ee, v242
	v_fmamk_f32 v214, v73, 0x3e0293ee, v242
	v_fmamk_f32 v215, v74, 0x3e0293ee, v242
	v_fmamk_f32 v216, v75, 0x3e0293ee, v242
	v_fmamk_f32 v209, v76, 0x3e0293ee, v242
	v_fmamk_f32 v222, v77, 0x3e0293ee, v242
	v_fmamk_f32 v223, v78, 0x3e0293ee, v242
	v_fmamk_f32 v208, v79, 0x3e0293ee, v242
	s_waitcnt lgkmcnt(0)
	s_barrier
	ds_read_b128 v[64:67], v192 offset:32768
	ds_read_b128 v[68:71], v192 offset:40960
	ds_read_b128 v[232:235], v200 offset:32768
	ds_read_b128 v[236:239], v200 offset:40960
	ds_read_b128 v[250:253], v199 offset:32768
	ds_read_b128 v[244:247], v199 offset:40960
	ds_read_b128 v[224:227], v198 offset:32768
	ds_read_b128 v[228:231], v198 offset:40960
	v_exp_f32_e32 v248, v208
	v_exp_f32_e32 v249, v209
	s_waitcnt lgkmcnt(6)
	v_mfma_f32_32x32x16_bf16 v[80:95], v[64:67], v[118:121], 0
	v_exp_f32_e32 v217, v217
	v_add_f32_e32 v208, v162, v177
	v_exp_f32_e32 v218, v218
	v_mfma_f32_32x32x16_bf16 v[64:79], v[68:71], v[118:121], 0
	v_add_f32_e32 v208, v163, v208
	v_exp_f32_e32 v219, v219
	v_add_f32_e32 v208, v176, v208
	v_exp_f32_e32 v220, v220
	v_add_f32_e32 v208, v164, v208
	s_waitcnt lgkmcnt(4)
	v_mfma_f32_32x32x16_bf16 v[80:95], v[232:235], v[114:117], v[80:95]
	ds_read_b128 v[232:235], v195 offset:32768
	v_exp_f32_e32 v221, v221
	v_add_f32_e32 v208, v175, v208
	v_exp_f32_e32 v210, v210
	v_add_f32_e32 v208, v165, v208
	v_mfma_f32_32x32x16_bf16 v[64:79], v[236:239], v[114:117], v[64:79]
	ds_read_b128 v[236:239], v195 offset:40960
	v_exp_f32_e32 v211, v211
	v_add_f32_e32 v208, v174, v208
	v_exp_f32_e32 v212, v212
	v_add_f32_e32 v208, v166, v208
	s_waitcnt lgkmcnt(4)
	v_mfma_f32_32x32x16_bf16 v[80:95], v[250:253], v[126:129], v[80:95]
	ds_read_b128 v[250:253], v193 offset:32768
	v_exp_f32_e32 v213, v213
	v_add_f32_e32 v208, v173, v208
	v_exp_f32_e32 v214, v214
	v_add_f32_e32 v208, v167, v208
	v_mfma_f32_32x32x16_bf16 v[64:79], v[244:247], v[126:129], v[64:79]
	ds_read_b128 v[244:247], v193 offset:40960
	v_exp_f32_e32 v215, v215
	v_add_f32_e32 v208, v172, v208
	v_exp_f32_e32 v216, v216
	v_add_f32_e32 v208, v168, v208
	s_waitcnt lgkmcnt(4)
	v_mfma_f32_32x32x16_bf16 v[80:95], v[224:227], v[122:125], v[80:95]
	ds_read_b128 v[224:227], v202 offset:32768
	v_exp_f32_e32 v222, v222
	v_add_f32_e32 v208, v171, v208
	v_exp_f32_e32 v223, v223
	v_add_f32_e32 v208, v169, v208
	v_mfma_f32_32x32x16_bf16 v[64:79], v[228:231], v[122:125], v[64:79]
	ds_read_b128 v[228:231], v202 offset:40960
	v_add_f32_e32 v208, v170, v208
	v_add_f32_e32 v208, v217, v208
	v_add_f32_e32 v208, v218, v208
	v_add_f32_e32 v208, v219, v208
	s_waitcnt lgkmcnt(4)
	v_mfma_f32_32x32x16_bf16 v[80:95], v[232:235], v[110:113], v[80:95]
	ds_read_b128 v[232:235], v201 offset:32768
	v_add_f32_e32 v208, v220, v208
	v_add_f32_e32 v208, v221, v208
	v_add_f32_e32 v208, v210, v208
	v_add_f32_e32 v208, v211, v208
	v_mfma_f32_32x32x16_bf16 v[64:79], v[236:239], v[110:113], v[64:79]
	ds_read_b128 v[236:239], v201 offset:40960
	v_add_f32_e32 v208, v212, v208
	v_add_f32_e32 v208, v213, v208
	v_add_f32_e32 v208, v214, v208
	v_add_f32_e32 v208, v215, v208
	s_waitcnt lgkmcnt(4)
	v_mfma_f32_32x32x16_bf16 v[80:95], v[250:253], v[106:109], v[80:95]
	v_add_f32_e32 v208, v216, v208
	v_add_f32_e32 v208, v249, v208
	v_add_f32_e32 v208, v222, v208
	v_add_f32_e32 v208, v223, v208
	v_mfma_f32_32x32x16_bf16 v[64:79], v[244:247], v[106:109], v[64:79]
	v_add_f32_e32 v208, v248, v208
	v_fma_f32 v185, v185, v206, v208
	v_cvt_pk_bf16_f32 v162, v162, v177
	v_cvt_pk_bf16_f32 v163, v163, v176
	s_waitcnt lgkmcnt(2)
	v_mfma_f32_32x32x16_bf16 v[80:95], v[224:227], v[102:105], v[80:95]
	v_cvt_pk_bf16_f32 v164, v164, v175
	v_cvt_pk_bf16_f32 v165, v165, v174
	v_cvt_pk_bf16_f32 v166, v166, v173
	v_cvt_pk_bf16_f32 v167, v167, v172
	v_mfma_f32_32x32x16_bf16 v[64:79], v[228:231], v[102:105], v[64:79]
	v_cvt_pk_bf16_f32 v168, v168, v171
	v_cvt_pk_bf16_f32 v169, v169, v170
	v_cvt_pk_bf16_f32 v170, v217, v218
	v_cvt_pk_bf16_f32 v171, v219, v220
	s_waitcnt lgkmcnt(0)
	v_mfma_f32_32x32x16_bf16 v[80:95], v[232:235], v[98:101], v[80:95]
	v_cvt_pk_bf16_f32 v172, v221, v210
	v_cvt_pk_bf16_f32 v173, v211, v212
	v_cvt_pk_bf16_f32 v174, v213, v214
	v_cvt_pk_bf16_f32 v175, v215, v216
	v_mfma_f32_32x32x16_bf16 v[64:79], v[236:239], v[98:101], v[64:79]
	v_cvt_pk_bf16_f32 v176, v249, v222
	v_cvt_pk_bf16_f32 v177, v223, v248
	ds_read_b64_tr_b16 v[210:211], v186 offset:0x0
	ds_read_b64_tr_b16 v[212:213], v186 offset:0x800
	ds_read_b64_tr_b16 v[214:215], v186 offset:0x200
	ds_read_b64_tr_b16 v[216:217], v186 offset:0xa00
	ds_read_b64_tr_b16 v[218:219], v186 offset:0x400
	ds_read_b64_tr_b16 v[220:221], v186 offset:0xc00
	ds_read_b64_tr_b16 v[222:223], v186 offset:0x600
	ds_read_b64_tr_b16 v[224:225], v186 offset:0xe00
	s_waitcnt vmcnt(1)
	ds_write_b128 v188, v[154:157] offset:49152
	s_waitcnt vmcnt(0)
	ds_write_b128 v189, v[158:161] offset:49152
	s_cmp_ge_u32 s34, s35
	s_cselect_b64 s[6:7], -1, 0
	s_cbranch_scc1 .LBB0_532
	global_load_dwordx4 v[130:133], v178, s[66:67]
	global_load_dwordx4 v[134:137], v178, s[98:99]
	global_load_dwordx4 v[138:141], v179, s[66:67]
	global_load_dwordx4 v[142:145], v179, s[98:99]
	s_add_u32 s66, s66, 0x4000
	s_addc_u32 s67, s67, 0
	s_add_u32 s98, s98, 0x4000
	s_addc_u32 s99, s99, 0

.Lattn_common_b:
	v_mfma_f32_32x32x16_bf16 v[48:63], v[166:169], v[214:217], v[48:63]
	ds_read_b64_tr_b16 v[214:215], v186 offset:0x2200
	ds_read_b64_tr_b16 v[216:217], v186 offset:0x2a00
	v_fmamk_f32 v80, v80, 0x3e0293ee, v242
	v_fmamk_f32 v81, v81, 0x3e0293ee, v242
	v_fmamk_f32 v82, v82, 0x3e0293ee, v242
	v_fmamk_f32 v83, v83, 0x3e0293ee, v242
	s_waitcnt lgkmcnt(4)
	v_mfma_f32_32x32x16_bf16 v[32:47], v[166:169], v[218:221], v[32:47]
	ds_read_b64_tr_b16 v[218:219], v186 offset:0x2400
	ds_read_b64_tr_b16 v[220:221], v186 offset:0x2c00
	v_fmamk_f32 v84, v84, 0x3e0293ee, v242
	v_fmamk_f32 v85, v85, 0x3e0293ee, v242
	v_fmamk_f32 v86, v86, 0x3e0293ee, v242
	v_fmamk_f32 v87, v87, 0x3e0293ee, v242
	v_fmamk_f32 v88, v88, 0x3e0293ee, v242
	v_fmamk_f32 v89, v89, 0x3e0293ee, v242
	v_mfma_f32_32x32x16_bf16 v[16:31], v[166:169], v[222:225], v[16:31]
	ds_read_b64_tr_b16 v[222:223], v186 offset:0x2600
	ds_read_b64_tr_b16 v[224:225], v186 offset:0x2e00
	v_fmamk_f32 v90, v90, 0x3e0293ee, v242
	v_fmamk_f32 v91, v91, 0x3e0293ee, v242
	v_fmamk_f32 v92, v92, 0x3e0293ee, v242
	v_fmamk_f32 v93, v93, 0x3e0293ee, v242
	v_fmamk_f32 v94, v94, 0x3e0293ee, v242
	v_fmamk_f32 v95, v95, 0x3e0293ee, v242
	s_waitcnt lgkmcnt(4)
	v_mfma_f32_32x32x16_bf16 v[0:15], v[170:173], v[210:213], v[0:15]
	ds_read_b64_tr_b16 v[210:211], v186 offset:0x3000
	ds_read_b64_tr_b16 v[212:213], v186 offset:0x3800
	v_exp_f32_e32 v207, v83
	v_exp_f32_e32 v163, v80
	v_exp_f32_e32 v164, v82
	v_mfma_f32_32x32x16_bf16 v[48:63], v[170:173], v[214:217], v[48:63]
	ds_read_b64_tr_b16 v[214:215], v186 offset:0x3200
	ds_read_b64_tr_b16 v[216:217], v186 offset:0x3a00
	v_exp_f32_e32 v165, v86
	v_exp_f32_e32 v166, v88
	v_exp_f32_e32 v167, v90
	s_waitcnt lgkmcnt(4)
	v_mfma_f32_32x32x16_bf16 v[32:47], v[170:173], v[218:221], v[32:47]
	ds_read_b64_tr_b16 v[218:219], v186 offset:0x3400
	ds_read_b64_tr_b16 v[220:221], v186 offset:0x3c00
	v_exp_f32_e32 v168, v92
	v_exp_f32_e32 v169, v94
	v_mfma_f32_32x32x16_bf16 v[16:31], v[170:173], v[222:225], v[16:31]
	ds_read_b64_tr_b16 v[222:223], v186 offset:0x3600
	ds_read_b64_tr_b16 v[224:225], v186 offset:0x3e00
	s_waitcnt lgkmcnt(4)
	v_mfma_f32_32x32x16_bf16 v[0:15], v[174:177], v[210:213], v[0:15]
	v_exp_f32_e32 v171, v93
	v_exp_f32_e32 v172, v95
	v_exp_f32_e32 v173, v89
	v_mfma_f32_32x32x16_bf16 v[48:63], v[174:177], v[214:217], v[48:63]
	v_exp_f32_e32 v210, v85
	s_waitcnt lgkmcnt(0)
	v_mfma_f32_32x32x16_bf16 v[32:47], v[174:177], v[218:221], v[32:47]
	v_mfma_f32_32x32x16_bf16 v[16:31], v[174:177], v[222:225], v[16:31]
	v_exp_f32_e32 v174, v91
	v_exp_f32_e32 v175, v87
	v_exp_f32_e32 v176, v84
	v_exp_f32_e32 v177, v81
	s_barrier
	v_cndmask_b32_e64 v203, v241, 1.0, s[42:43]
	ds_write_b128 v190, v[146:149] offset:16384
	ds_write_b128 v191, v[150:153] offset:16384
	s_cmp_lg_u64 s[42:43], 0
	s_cbranch_scc1 .LBB0_536
	s_and_saveexec_b64 s[8:9], s[40:41]
	ds_write_b32 v184, v203 offset:128
	s_or_b64 exec, exec, s[8:9]
	s_waitcnt lgkmcnt(0)
	ds_read_b128 v[146:149], v182 offset:224
	ds_read_b128 v[150:153], v182 offset:192
	ds_read_b128 v[154:157], v182 offset:160
	ds_read_b128 v[158:161], v182 offset:128
	s_waitcnt lgkmcnt(3)
	v_pk_mul_f32 v[14:15], v[14:15], v[148:149]
	s_waitcnt lgkmcnt(2)
	v_pk_mul_f32 v[10:11], v[10:11], v[152:153]
	s_waitcnt lgkmcnt(1)
	v_pk_mul_f32 v[6:7], v[6:7], v[156:157]
	s_waitcnt lgkmcnt(0)
	v_pk_mul_f32 v[2:3], v[2:3], v[160:161]
	v_pk_mul_f32 v[12:13], v[12:13], v[146:147]
	v_pk_mul_f32 v[8:9], v[8:9], v[150:151]
	v_pk_mul_f32 v[4:5], v[4:5], v[154:155]
	v_pk_mul_f32 v[0:1], v[0:1], v[158:159]
	v_pk_mul_f32 v[62:63], v[62:63], v[148:149]
	v_pk_mul_f32 v[58:59], v[58:59], v[152:153]
	v_pk_mul_f32 v[54:55], v[54:55], v[156:157]
	v_pk_mul_f32 v[50:51], v[50:51], v[160:161]
	v_pk_mul_f32 v[60:61], v[60:61], v[146:147]
	v_pk_mul_f32 v[56:57], v[56:57], v[150:151]
	v_pk_mul_f32 v[52:53], v[52:53], v[154:155]
	v_pk_mul_f32 v[48:49], v[48:49], v[158:159]
	v_pk_mul_f32 v[46:47], v[46:47], v[148:149]
	v_pk_mul_f32 v[42:43], v[42:43], v[152:153]
	v_pk_mul_f32 v[38:39], v[38:39], v[156:157]
	v_pk_mul_f32 v[34:35], v[34:35], v[160:161]
	v_pk_mul_f32 v[44:45], v[44:45], v[146:147]
	v_pk_mul_f32 v[40:41], v[40:41], v[150:151]
	v_pk_mul_f32 v[36:37], v[36:37], v[154:155]
	v_pk_mul_f32 v[32:33], v[32:33], v[158:159]
	v_pk_mul_f32 v[30:31], v[30:31], v[148:149]
	v_pk_mul_f32 v[26:27], v[26:27], v[152:153]
	v_pk_mul_f32 v[22:23], v[22:23], v[156:157]
	v_pk_mul_f32 v[18:19], v[18:19], v[160:161]
	v_pk_mul_f32 v[28:29], v[28:29], v[146:147]
	v_pk_mul_f32 v[24:25], v[24:25], v[150:151]
	v_pk_mul_f32 v[20:21], v[20:21], v[154:155]
	v_pk_mul_f32 v[16:17], v[16:17], v[158:159]
.LBB0_536:
	v_pk_fma_f32 v[160:161], v[64:65], s[88:89], v[242:243] op_sel_hi:[1,0,0]
	v_pk_fma_f32 v[158:159], v[66:67], s[88:89], v[242:243] op_sel_hi:[1,0,0]
	v_pk_fma_f32 v[154:155], v[68:69], s[88:89], v[242:243] op_sel_hi:[1,0,0]
	v_pk_fma_f32 v[150:151], v[70:71], s[88:89], v[242:243] op_sel_hi:[1,0,0]
	v_pk_fma_f32 v[148:149], v[72:73], s[88:89], v[242:243] op_sel_hi:[1,0,0]
	v_pk_fma_f32 v[156:157], v[74:75], s[88:89], v[242:243] op_sel_hi:[1,0,0]
	v_pk_fma_f32 v[152:153], v[76:77], s[88:89], v[242:243] op_sel_hi:[1,0,0]
	v_pk_fma_f32 v[146:147], v[78:79], s[88:89], v[242:243] op_sel_hi:[1,0,0]
	s_add_i32 s34, s34, 2
	s_and_b64 vcc, exec, s[6:7]
	s_waitcnt lgkmcnt(0)
	s_barrier
	s_cbranch_vccnz .LBB0_538
	s_branch .LBB0_526
.LBB0_538:
	v_mov_b32_e32 v162, v203
	v_mov_b32_e32 v170, v243
	v_mov_b32_e32 v64, v185
	s_nop 1
	v_permlane32_swap_b32_e32 v185, v64
	v_add_f32_e32 v185, v185, v64
	ds_read_b128 v[64:67], v192 offset:49152
	ds_read_b128 v[68:71], v192 offset:57344
	s_waitcnt lgkmcnt(1)
	v_mfma_f32_32x32x16_bf16 v[80:95], v[64:67], v[118:121], 0
	s_waitcnt lgkmcnt(0)
	v_mfma_f32_32x32x16_bf16 v[64:79], v[68:71], v[118:121], 0
	ds_read_b128 v[118:121], v200 offset:49152
	ds_read_b128 v[130:133], v200 offset:57344
	s_waitcnt lgkmcnt(1)
	v_mfma_f32_32x32x16_bf16 v[80:95], v[118:121], v[114:117], v[80:95]
	s_waitcnt lgkmcnt(0)
	v_mfma_f32_32x32x16_bf16 v[64:79], v[130:133], v[114:117], v[64:79]
	ds_read_b128 v[114:117], v199 offset:49152
	ds_read_b128 v[118:121], v199 offset:57344
	s_waitcnt lgkmcnt(1)
	v_mfma_f32_32x32x16_bf16 v[80:95], v[114:117], v[126:129], v[80:95]
	s_waitcnt lgkmcnt(0)
	v_mfma_f32_32x32x16_bf16 v[64:79], v[118:121], v[126:129], v[64:79]
	ds_read_b128 v[114:117], v198 offset:49152
	ds_read_b128 v[118:121], v198 offset:57344
	s_waitcnt lgkmcnt(1)
	v_mfma_f32_32x32x16_bf16 v[80:95], v[114:117], v[122:125], v[80:95]
	s_waitcnt lgkmcnt(0)
	v_mfma_f32_32x32x16_bf16 v[64:79], v[118:121], v[122:125], v[64:79]
	ds_read_b128 v[114:117], v195 offset:49152
	ds_read_b128 v[118:121], v195 offset:57344
	v_exp_f32_e32 v122, v146
	v_exp_f32_e32 v123, v147
	s_waitcnt lgkmcnt(1)
	v_mfma_f32_32x32x16_bf16 v[80:95], v[114:117], v[110:113], v[80:95]
	s_waitcnt lgkmcnt(0)
	v_mfma_f32_32x32x16_bf16 v[64:79], v[118:121], v[110:113], v[64:79]
	ds_read_b128 v[110:113], v193 offset:49152
	ds_read_b128 v[114:117], v193 offset:57344
	v_exp_f32_e32 v118, v156
	v_exp_f32_e32 v119, v157
	v_exp_f32_e32 v120, v152
	v_exp_f32_e32 v121, v153
	s_waitcnt lgkmcnt(1)
	v_mfma_f32_32x32x16_bf16 v[80:95], v[110:113], v[106:109], v[80:95]
	s_waitcnt lgkmcnt(0)
	v_mfma_f32_32x32x16_bf16 v[64:79], v[114:117], v[106:109], v[64:79]
	ds_read_b128 v[106:109], v202 offset:49152
	ds_read_b128 v[110:113], v202 offset:57344
	v_exp_f32_e32 v114, v150
	v_exp_f32_e32 v115, v151
	v_exp_f32_e32 v116, v148
	v_exp_f32_e32 v117, v149
	s_waitcnt lgkmcnt(1)
	v_mfma_f32_32x32x16_bf16 v[80:95], v[106:109], v[102:105], v[80:95]
	s_waitcnt lgkmcnt(0)
	v_mfma_f32_32x32x16_bf16 v[64:79], v[110:113], v[102:105], v[64:79]
	ds_read_b128 v[102:105], v201 offset:49152
	ds_read_b128 v[106:109], v201 offset:57344
	v_exp_f32_e32 v110, v158
	v_exp_f32_e32 v111, v159
	v_exp_f32_e32 v112, v154
	v_exp_f32_e32 v113, v155
	s_waitcnt lgkmcnt(1)
	v_mfma_f32_32x32x16_bf16 v[80:95], v[102:105], v[98:101], v[80:95]
	s_waitcnt lgkmcnt(0)
	v_mfma_f32_32x32x16_bf16 v[64:79], v[106:109], v[98:101], v[64:79]
	v_add_f32_e32 v98, 0, v163
	v_add_f32_e32 v98, v177, v98
	v_add_f32_e32 v98, v164, v98
	v_add_f32_e32 v98, v207, v98
	v_add_f32_e32 v98, v176, v98
	v_add_f32_e32 v98, v210, v98
	v_add_f32_e32 v98, v165, v98
	v_add_f32_e32 v98, v175, v98
	v_add_f32_e32 v98, v166, v98
	v_add_f32_e32 v98, v173, v98
	v_add_f32_e32 v98, v167, v98
	v_add_f32_e32 v98, v174, v98
	v_exp_f32_e32 v108, v160
	v_add_f32_e32 v98, v168, v98
	v_exp_f32_e32 v109, v161
	v_add_f32_e32 v98, v171, v98
	v_add_f32_e32 v98, v169, v98
	v_add_f32_e32 v98, v172, v98
	v_add_f32_e32 v98, v108, v98
	v_add_f32_e32 v98, v109, v98
	v_add_f32_e32 v98, v110, v98
	v_add_f32_e32 v98, v111, v98
	v_add_f32_e32 v98, v112, v98
	v_add_f32_e32 v98, v113, v98
	v_add_f32_e32 v98, v114, v98
	v_add_f32_e32 v98, v115, v98
	v_add_f32_e32 v98, v116, v98
	v_add_f32_e32 v98, v117, v98
	v_add_f32_e32 v98, v118, v98
	v_add_f32_e32 v98, v119, v98
	v_add_f32_e32 v98, v120, v98
	v_add_f32_e32 v98, v121, v98
	v_add_f32_e32 v98, v122, v98
	v_add_f32_e32 v98, v123, v98
	v_mov_b32_e32 v99, v98
	v_cvt_pk_bf16_f32 v100, v163, v177
	v_cvt_pk_bf16_f32 v101, v164, v207
	v_cvt_pk_bf16_f32 v102, v176, v210
	v_cvt_pk_bf16_f32 v103, v165, v175
	s_nop 1
	v_permlane32_swap_b32_e32 v98, v99
	v_cvt_pk_bf16_f32 v104, v166, v173
	v_cvt_pk_bf16_f32 v105, v167, v174
	v_cvt_pk_bf16_f32 v106, v168, v171
	v_cvt_pk_bf16_f32 v107, v169, v172
	v_cvt_pk_bf16_f32 v108, v108, v109
	v_cvt_pk_bf16_f32 v109, v110, v111
	v_cvt_pk_bf16_f32 v110, v112, v113
	v_cvt_pk_bf16_f32 v111, v114, v115
	v_cvt_pk_bf16_f32 v112, v116, v117
	v_cvt_pk_bf16_f32 v113, v118, v119
	v_cvt_pk_bf16_f32 v114, v120, v121
	v_cvt_pk_bf16_f32 v115, v122, v123
	s_nop 0
	ds_read_b64_tr_b16 v[116:117], v187 offset:0
	ds_read_b64_tr_b16 v[118:119], v187 offset:0x800
	ds_read_b64_tr_b16 v[120:121], v187 offset:0x1000
	ds_read_b64_tr_b16 v[122:123], v187 offset:0x1800
	ds_read_b64_tr_b16 v[124:125], v187 offset:0x2000
	ds_read_b64_tr_b16 v[126:127], v187 offset:0x2800
	ds_read_b64_tr_b16 v[128:129], v187 offset:0x3000
	ds_read_b64_tr_b16 v[130:131], v187 offset:0x3800
	s_waitcnt lgkmcnt(0)
	s_nop 0
	v_mfma_f32_32x32x16_bf16 v[0:15], v[100:103], v[116:119], v[0:15]
	ds_read_b64_tr_b16 v[116:117], v187 offset:0x200
	ds_read_b64_tr_b16 v[118:119], v187 offset:0xa00
	v_mfma_f32_32x32x16_bf16 v[0:15], v[104:107], v[120:123], v[0:15]
	ds_read_b64_tr_b16 v[120:121], v187 offset:0x1200
	ds_read_b64_tr_b16 v[122:123], v187 offset:0x1a00
	v_mfma_f32_32x32x16_bf16 v[0:15], v[108:111], v[124:127], v[0:15]
	ds_read_b64_tr_b16 v[124:125], v187 offset:0x2200
	ds_read_b64_tr_b16 v[126:127], v187 offset:0x2a00
	v_mfma_f32_32x32x16_bf16 v[0:15], v[112:115], v[128:131], v[0:15]
	ds_read_b64_tr_b16 v[128:129], v187 offset:0x3200
	ds_read_b64_tr_b16 v[130:131], v187 offset:0x3a00
	s_waitcnt lgkmcnt(0)
	v_mfma_f32_32x32x16_bf16 v[48:63], v[100:103], v[116:119], v[48:63]
	ds_read_b64_tr_b16 v[116:117], v187 offset:0x400
	ds_read_b64_tr_b16 v[118:119], v187 offset:0xc00
	v_mfma_f32_32x32x16_bf16 v[48:63], v[104:107], v[120:123], v[48:63]
	ds_read_b64_tr_b16 v[120:121], v187 offset:0x1400
	ds_read_b64_tr_b16 v[122:123], v187 offset:0x1c00
	v_mfma_f32_32x32x16_bf16 v[48:63], v[108:111], v[124:127], v[48:63]
	ds_read_b64_tr_b16 v[124:125], v187 offset:0x2400
	ds_read_b64_tr_b16 v[126:127], v187 offset:0x2c00
	v_mfma_f32_32x32x16_bf16 v[48:63], v[112:115], v[128:131], v[48:63]
	ds_read_b64_tr_b16 v[128:129], v187 offset:0x3400
	ds_read_b64_tr_b16 v[130:131], v187 offset:0x3c00
	s_waitcnt lgkmcnt(0)
	v_mfma_f32_32x32x16_bf16 v[32:47], v[100:103], v[116:119], v[32:47]
	ds_read_b64_tr_b16 v[116:117], v187 offset:0x600
	ds_read_b64_tr_b16 v[118:119], v187 offset:0xe00
	v_mfma_f32_32x32x16_bf16 v[32:47], v[104:107], v[120:123], v[32:47]
	ds_read_b64_tr_b16 v[120:121], v187 offset:0x1600
	ds_read_b64_tr_b16 v[122:123], v187 offset:0x1e00
	v_mfma_f32_32x32x16_bf16 v[32:47], v[108:111], v[124:127], v[32:47]
	ds_read_b64_tr_b16 v[124:125], v187 offset:0x2600
	ds_read_b64_tr_b16 v[126:127], v187 offset:0x2e00
	v_mfma_f32_32x32x16_bf16 v[32:47], v[112:115], v[128:131], v[32:47]
	ds_read_b64_tr_b16 v[128:129], v187 offset:0x3600
	ds_read_b64_tr_b16 v[130:131], v187 offset:0x3e00
	s_waitcnt lgkmcnt(0)
	v_mfma_f32_32x32x16_bf16 v[16:31], v[100:103], v[116:119], v[16:31]
	v_max_f32_e32 v100, v81, v81
	v_max_f32_e32 v101, v80, v80
	v_max_f32_e32 v100, v101, v100
	v_max3_f32 v100, v100, v82, v83
	v_max3_f32 v100, v100, v84, v85
	v_max3_f32 v100, v100, v86, v87
	v_max3_f32 v100, v100, v88, v89
	v_max3_f32 v100, v100, v90, v91
	v_max3_f32 v100, v100, v92, v93
	v_mfma_f32_32x32x16_bf16 v[16:31], v[104:107], v[120:123], v[16:31]
	v_max3_f32 v100, v100, v94, v95
	v_max3_f32 v100, v100, v64, v65
	v_max3_f32 v100, v100, v66, v67
	v_max3_f32 v100, v100, v68, v69
	v_max3_f32 v100, v100, v70, v71
	v_max3_f32 v100, v100, v72, v73
	v_max3_f32 v100, v100, v74, v75
	v_max3_f32 v100, v100, v76, v77
	v_mfma_f32_32x32x16_bf16 v[16:31], v[108:111], v[124:127], v[16:31]
	v_max3_f32 v100, v100, v78, v79
	v_mov_b32_e32 v101, v100
	s_nop 1
	v_permlane32_swap_b32_e32 v100, v101
	v_max_f32_e32 v101, v101, v101
	v_max_f32_e32 v100, v100, v100
	v_max_f32_e32 v100, v100, v101
	v_sub_f32_e32 v101, v100, v170
	v_cmp_ge_f32_e32 vcc, s92, v101
	v_max_f32_e32 v101, v170, v170
	v_max_f32_e32 v101, v101, v100
	v_mfma_f32_32x32x16_bf16 v[16:31], v[112:115], v[128:131], v[16:31]
	v_sub_f32_e32 v100, v170, v101
	v_mul_f32_e32 v100, 0x3e0293ee, v100
	v_exp_f32_e32 v100, v100
	s_cmp_eq_u64 vcc, exec
	s_cselect_b64 s[42:43], -1, 0
	v_cndmask_b32_e64 v100, v100, 1.0, s[42:43]
	v_cmp_gt_f32_e32 vcc, 1.0, v100
	s_barrier
	s_cbranch_vccz .LBB0_542
	s_and_saveexec_b64 s[6:7], s[40:41]
	ds_write_b32 v184, v100 offset:128
	s_or_b64 exec, exec, s[6:7]
	s_waitcnt lgkmcnt(0)
	ds_read_b128 v[102:105], v182 offset:224
	ds_read_b128 v[106:109], v182 offset:192
	ds_read_b128 v[110:113], v182 offset:160
	ds_read_b128 v[114:117], v182 offset:128
	s_waitcnt lgkmcnt(3)
	v_pk_mul_f32 v[14:15], v[14:15], v[104:105]
	s_waitcnt lgkmcnt(2)
	v_pk_mul_f32 v[10:11], v[10:11], v[108:109]
	s_waitcnt lgkmcnt(1)
	v_pk_mul_f32 v[6:7], v[6:7], v[112:113]
	s_waitcnt lgkmcnt(0)
	v_pk_mul_f32 v[2:3], v[2:3], v[116:117]
	v_pk_mul_f32 v[12:13], v[12:13], v[102:103]
	v_pk_mul_f32 v[8:9], v[8:9], v[106:107]
	v_pk_mul_f32 v[4:5], v[4:5], v[110:111]
	v_pk_mul_f32 v[0:1], v[0:1], v[114:115]
	v_pk_mul_f32 v[62:63], v[62:63], v[104:105]
	v_pk_mul_f32 v[58:59], v[58:59], v[108:109]
	v_pk_mul_f32 v[54:55], v[54:55], v[112:113]
	v_pk_mul_f32 v[50:51], v[50:51], v[116:117]
	v_pk_mul_f32 v[60:61], v[60:61], v[102:103]
	v_pk_mul_f32 v[56:57], v[56:57], v[106:107]
	v_pk_mul_f32 v[52:53], v[52:53], v[110:111]
	v_pk_mul_f32 v[48:49], v[48:49], v[114:115]
	v_pk_mul_f32 v[46:47], v[46:47], v[104:105]
	v_pk_mul_f32 v[42:43], v[42:43], v[108:109]
	v_pk_mul_f32 v[38:39], v[38:39], v[112:113]
	v_pk_mul_f32 v[34:35], v[34:35], v[116:117]
	v_pk_mul_f32 v[44:45], v[44:45], v[102:103]
	v_pk_mul_f32 v[40:41], v[40:41], v[106:107]
	v_pk_mul_f32 v[36:37], v[36:37], v[110:111]
	v_pk_mul_f32 v[32:33], v[32:33], v[114:115]
	v_pk_mul_f32 v[30:31], v[30:31], v[104:105]
	v_pk_mul_f32 v[26:27], v[26:27], v[108:109]
	v_pk_mul_f32 v[22:23], v[22:23], v[112:113]
	v_pk_mul_f32 v[18:19], v[18:19], v[116:117]
	v_pk_mul_f32 v[28:29], v[28:29], v[102:103]
	v_pk_mul_f32 v[24:25], v[24:25], v[106:107]
	v_pk_mul_f32 v[20:21], v[20:21], v[110:111]
	v_pk_mul_f32 v[16:17], v[16:17], v[114:115]
